# attention loop head aligned to a 64-byte boundary (six s_nop before the loop label)
# baseline (speedup 1.0000x reference)
;   #define DMA_K(t,s3) glds16(ksrc+(long)(t)*KVBLK*DM,(unsigned)__builtin_amdgcn_readfirstlane(kdst+(s3)*SLOTB))
;   #define DMA_V(t,s3) do{ const unsigned vd_=(unsigned)__builtin_amdgcn_readfirstlane(vdst+(s3)*VSLOTB); glds16(vsrc+(long)(t)*KVBLK*DM,vd_); glds16(vsrc+(long)(t)*KVBLK*DM+64,(unsigned)__builtin_amdgcn_readfirstlane(vd_+8192)); }while(0)
; template<int THRL> __device__ __forceinline__ void attn_unit(int qb,const bf16*Q,const bf16*__restrict__ K,const bf16*__restrict__ V,bf16*O,char*shm){
;     ...
;   for(int t=0;t<NT;++t){
;     if(t+2<NT){DMA_K(t+2,c2);DMA_V(t+2,c2);}
;     bf16x8 kf[8]; kload8(kf,kp0+c0*SLOTB);
.LBB0_366:
	s_lshl_b32 s14, s34, 14
	v_add_u32_e32 v193, s14, v190
	s_nop 0
	s_nop 0
	s_nop 0
	s_nop 0
	s_nop 0
	s_nop 0
